# k49: k48 + P0 cache K/V conversion de-serialised further (three straight-line rounds, double-buffered loads, unconditional clamped loads with masked stores)
# speedup vs baseline: 1.0010x; 1.0010x over previous
; __device__ __forceinline__ unsigned pk2(float lo, float hi) { typedef __bf16 bf16x2_t_ __attribute__((ext_vector_type(2))); f32x2 v = {lo, hi}; return __builtin_bit_cast(unsigned, __builtin_convertvector(v, bf16x2_t_)); }
; __global__ void __launch_bounds__(NTHR, 2) hymba_fwd(Params P) {
;     ...
;         const int gt = (bq >= 0) ? bq * NTHR + tid : 0x7fffffff - Gq * NTHR, NGT = Gq * NTHR;
; #pragma unroll 4
;         for (int i = gt; i < NB * PAST * 64; i += NGT) { const int row = i >> 6, ch = i & 63, b = row >> 11, j = row & 2047;
;             const f32x4 k0 = *(const f32x4*)(P.cache_k + (size_t)row * 512 + ch * 8), k1 = *(const f32x4*)(P.cache_k + (size_t)row * 512 + ch * 8 + 4);
;             const f32x4 v0 = *(const f32x4*)(P.cache_v + (size_t)row * 512 + ch * 8), v1 = *(const f32x4*)(P.cache_v + (size_t)row * 512 + ch * 8 + 4);
;             *(u32x4*)(KS + (size_t)(b * SKV + j) * 512 + ch * 8) = (u32x4){pk2(k0[0], k0[1]), pk2(k0[2], k0[3]), pk2(k1[0], k1[1]), pk2(k1[2], k1[3])};
;             *(u32x4*)(VS + (size_t)(b * SKV + j) * 512 + ch * 8) = (u32x4){pk2(v0[0], v0[1]), pk2(v0[2], v0[3]), pk2(v1[0], v1[1]), pk2(v1[2], v1[3])}; }
.LBB0_65:
	s_waitcnt lgkmcnt(0)
	s_add_u32 s54, s92, 0x25000000
	s_addc_u32 s55, s93, 0
	s_add_u32 s56, s92, 0x26100000
	s_addc_u32 s57, s93, 0
	s_add_i32 s12, s2, 0xffffffb0
	s_add_i32 s3, s2, 0xb0
	s_cmp_lt_i32 s2, 48
	s_cselect_b32 s12, s3, s12
	s_cmp_gt_i32 s12, -1
	s_cselect_b64 s[0:1], -1, 0
	s_movk_i32 s3, 0xe0
	s_lshl_b32 s10, s3, 9
	s_xor_b32 s4, s10, 0x7fffffff
	v_lshl_add_u32 v1, s12, 9, v1
	v_mov_b32_e32 v2, s4
	v_cndmask_b32_e64 v2, v2, v1, s[0:1]
	s_mov_b32 s0, 0x100000
	s_movk_i32 s11, 0x840
	v_cmp_gt_i32_e32 vcc, s0, v2
	s_and_saveexec_b64 s[4:5], vcc
	s_cbranch_execz .LBB0_73
	s_mov_b64 s[14:15], exec
	s_mov_b32 s3, 0xfffff
	v_mov_b32_e32 v3, v2
	v_add_u32_e32 v61, s10, v3
	v_add_u32_e32 v62, s10, v61
	v_add_u32_e32 v63, s10, v62
	s_mov_b64 exec, s[14:15]
	v_cmp_gt_i32_e64 s[6:7], s0, v3
	v_cmp_gt_i32_e64 s[16:17], s0, v61
	v_cmp_gt_i32_e64 s[18:19], s0, v62
	v_cmp_gt_i32_e64 s[20:21], s0, v63
	s_nop 1
	v_min_i32_e32 v64, s3, v3
	v_lshlrev_b32_e32 v64, 5, v64
	global_load_dwordx4 v[72:75], v64, s[40:41]
	global_load_dwordx4 v[76:79], v64, s[40:41] offset:16
	global_load_dwordx4 v[80:83], v64, s[42:43]
	global_load_dwordx4 v[84:87], v64, s[42:43] offset:16
	v_min_i32_e32 v65, s3, v61
	v_lshlrev_b32_e32 v65, 5, v65
	global_load_dwordx4 v[88:91], v65, s[40:41]
	global_load_dwordx4 v[92:95], v65, s[40:41] offset:16
	global_load_dwordx4 v[96:99], v65, s[42:43]
	global_load_dwordx4 v[100:103], v65, s[42:43] offset:16
	v_min_i32_e32 v66, s3, v62
	v_lshlrev_b32_e32 v66, 5, v66
	global_load_dwordx4 v[104:107], v66, s[40:41]
	global_load_dwordx4 v[108:111], v66, s[40:41] offset:16
	global_load_dwordx4 v[112:115], v66, s[42:43]
	global_load_dwordx4 v[116:119], v66, s[42:43] offset:16
	v_min_i32_e32 v67, s3, v63
	v_lshlrev_b32_e32 v67, 5, v67
	global_load_dwordx4 v[120:123], v67, s[40:41]
	global_load_dwordx4 v[124:127], v67, s[40:41] offset:16
	global_load_dwordx4 v[128:131], v67, s[42:43]
	global_load_dwordx4 v[132:135], v67, s[42:43] offset:16
	s_mov_b64 exec, s[14:15]
	v_ashrrev_i32_e32 v242, 17, v3
	v_bfe_u32 v243, v3, 6, 11
	v_mad_u32_u24 v243, v242, s11, v243
	v_and_b32_e32 v242, 63, v3
	v_lshlrev_b32_e32 v242, 4, v242
	v_lshl_add_u32 v68, v243, 10, v242
	v_ashrrev_i32_e32 v242, 17, v61
	v_bfe_u32 v243, v61, 6, 11
	v_mad_u32_u24 v243, v242, s11, v243
	v_and_b32_e32 v242, 63, v61
	v_lshlrev_b32_e32 v242, 4, v242
	v_lshl_add_u32 v69, v243, 10, v242
	v_ashrrev_i32_e32 v242, 17, v62
	v_bfe_u32 v243, v62, 6, 11
	v_mad_u32_u24 v243, v242, s11, v243
	v_and_b32_e32 v242, 63, v62
	v_lshlrev_b32_e32 v242, 4, v242
	v_lshl_add_u32 v70, v243, 10, v242
	v_ashrrev_i32_e32 v242, 17, v63
	v_bfe_u32 v243, v63, 6, 11
	v_mad_u32_u24 v243, v242, s11, v243
	v_and_b32_e32 v242, 63, v63
	v_lshlrev_b32_e32 v242, 4, v242
	v_lshl_add_u32 v71, v243, 10, v242
	v_add_u32_e32 v200, s10, v63
	v_add_u32_e32 v201, s10, v200
	v_add_u32_e32 v203, s10, v201
	v_add_u32_e32 v204, s10, v203
	s_mov_b64 exec, s[14:15]
	v_cmp_gt_i32_e64 s[22:23], s0, v200
	v_cmp_gt_i32_e64 s[24:25], s0, v201
	v_cmp_gt_i32_e64 s[26:27], s0, v203
	v_cmp_gt_i32_e64 s[30:31], s0, v204
	s_nop 1
	v_min_i32_e32 v64, s3, v200
	v_lshlrev_b32_e32 v64, 5, v64
	global_load_dwordx4 v[136:139], v64, s[40:41]
	global_load_dwordx4 v[140:143], v64, s[40:41] offset:16
	global_load_dwordx4 v[144:147], v64, s[42:43]
	global_load_dwordx4 v[148:151], v64, s[42:43] offset:16
	v_min_i32_e32 v65, s3, v201
	v_lshlrev_b32_e32 v65, 5, v65
	global_load_dwordx4 v[152:155], v65, s[40:41]
	global_load_dwordx4 v[156:159], v65, s[40:41] offset:16
	global_load_dwordx4 v[160:163], v65, s[42:43]
	global_load_dwordx4 v[164:167], v65, s[42:43] offset:16
	v_min_i32_e32 v66, s3, v203
	v_lshlrev_b32_e32 v66, 5, v66
	global_load_dwordx4 v[168:171], v66, s[40:41]
	global_load_dwordx4 v[172:175], v66, s[40:41] offset:16
	global_load_dwordx4 v[176:179], v66, s[42:43]
	global_load_dwordx4 v[180:183], v66, s[42:43] offset:16
	v_min_i32_e32 v67, s3, v204
	v_lshlrev_b32_e32 v67, 5, v67
	global_load_dwordx4 v[184:187], v67, s[40:41]
	global_load_dwordx4 v[188:191], v67, s[40:41] offset:16
	global_load_dwordx4 v[192:195], v67, s[42:43]
	global_load_dwordx4 v[196:199], v67, s[42:43] offset:16
	s_mov_b64 exec, s[14:15]
	v_ashrrev_i32_e32 v242, 17, v200
	v_bfe_u32 v243, v200, 6, 11
	v_mad_u32_u24 v243, v242, s11, v243
	v_and_b32_e32 v242, 63, v200
	v_lshlrev_b32_e32 v242, 4, v242
	v_lshl_add_u32 v205, v243, 10, v242
	v_ashrrev_i32_e32 v242, 17, v201
	v_bfe_u32 v243, v201, 6, 11
	v_mad_u32_u24 v243, v242, s11, v243
	v_and_b32_e32 v242, 63, v201
	v_lshlrev_b32_e32 v242, 4, v242
	v_lshl_add_u32 v206, v243, 10, v242
	v_ashrrev_i32_e32 v242, 17, v203
	v_bfe_u32 v243, v203, 6, 11
	v_mad_u32_u24 v243, v242, s11, v243
	v_and_b32_e32 v242, 63, v203
	v_lshlrev_b32_e32 v242, 4, v242
	v_lshl_add_u32 v207, v243, 10, v242
	v_ashrrev_i32_e32 v242, 17, v204
	v_bfe_u32 v243, v204, 6, 11
	v_mad_u32_u24 v243, v242, s11, v243
	v_and_b32_e32 v242, 63, v204
	v_lshlrev_b32_e32 v242, 4, v242
	v_lshl_add_u32 v209, v243, 10, v242
	s_waitcnt vmcnt(28)
	v_cvt_pk_bf16_f32 v210, v72, v73
	v_cvt_pk_bf16_f32 v211, v74, v75
	v_cvt_pk_bf16_f32 v212, v76, v77
	v_cvt_pk_bf16_f32 v213, v78, v79
	v_cvt_pk_bf16_f32 v214, v80, v81
	v_cvt_pk_bf16_f32 v215, v82, v83
	v_cvt_pk_bf16_f32 v216, v84, v85
	v_cvt_pk_bf16_f32 v217, v86, v87
	s_waitcnt vmcnt(24)
	v_cvt_pk_bf16_f32 v218, v88, v89
	v_cvt_pk_bf16_f32 v219, v90, v91
	v_cvt_pk_bf16_f32 v220, v92, v93
	v_cvt_pk_bf16_f32 v221, v94, v95
	v_cvt_pk_bf16_f32 v222, v96, v97
	v_cvt_pk_bf16_f32 v223, v98, v99
	v_cvt_pk_bf16_f32 v224, v100, v101
	v_cvt_pk_bf16_f32 v225, v102, v103
	s_waitcnt vmcnt(20)
; __device__ __forceinline__ unsigned pk2(float lo, float hi) { typedef __bf16 bf16x2_t_ __attribute__((ext_vector_type(2))); f32x2 v = {lo, hi}; return __builtin_bit_cast(unsigned, __builtin_convertvector(v, bf16x2_t_)); }
; __global__ void __launch_bounds__(NTHR, 2) hymba_fwd(Params P) {
;     ...
;         const int gt = (bq >= 0) ? bq * NTHR + tid : 0x7fffffff - Gq * NTHR, NGT = Gq * NTHR;
; #pragma unroll 4
;         for (int i = gt; i < NB * PAST * 64; i += NGT) { const int row = i >> 6, ch = i & 63, b = row >> 11, j = row & 2047;
;             const f32x4 k0 = *(const f32x4*)(P.cache_k + (size_t)row * 512 + ch * 8), k1 = *(const f32x4*)(P.cache_k + (size_t)row * 512 + ch * 8 + 4);
;             const f32x4 v0 = *(const f32x4*)(P.cache_v + (size_t)row * 512 + ch * 8), v1 = *(const f32x4*)(P.cache_v + (size_t)row * 512 + ch * 8 + 4);
;             *(u32x4*)(KS + (size_t)(b * SKV + j) * 512 + ch * 8) = (u32x4){pk2(k0[0], k0[1]), pk2(k0[2], k0[3]), pk2(k1[0], k1[1]), pk2(k1[2], k1[3])};
;             *(u32x4*)(VS + (size_t)(b * SKV + j) * 512 + ch * 8) = (u32x4){pk2(v0[0], v0[1]), pk2(v0[2], v0[3]), pk2(v1[0], v1[1]), pk2(v1[2], v1[3])}; }
	v_cvt_pk_bf16_f32 v226, v104, v105
	v_cvt_pk_bf16_f32 v227, v106, v107
	v_cvt_pk_bf16_f32 v228, v108, v109
	v_cvt_pk_bf16_f32 v229, v110, v111
	v_cvt_pk_bf16_f32 v230, v112, v113
	v_cvt_pk_bf16_f32 v231, v114, v115
	v_cvt_pk_bf16_f32 v232, v116, v117
	v_cvt_pk_bf16_f32 v233, v118, v119
	s_waitcnt vmcnt(16)
	v_cvt_pk_bf16_f32 v234, v120, v121
	v_cvt_pk_bf16_f32 v235, v122, v123
	v_cvt_pk_bf16_f32 v236, v124, v125
	v_cvt_pk_bf16_f32 v237, v126, v127
	v_cvt_pk_bf16_f32 v238, v128, v129
	v_cvt_pk_bf16_f32 v239, v130, v131
	v_cvt_pk_bf16_f32 v240, v132, v133
	v_cvt_pk_bf16_f32 v241, v134, v135
	s_mov_b64 exec, s[6:7]
	global_store_dwordx4 v68, v[210:213], s[54:55]
	global_store_dwordx4 v68, v[214:217], s[56:57]
	s_mov_b64 exec, s[16:17]
	global_store_dwordx4 v69, v[218:221], s[54:55]
	global_store_dwordx4 v69, v[222:225], s[56:57]
	s_mov_b64 exec, s[18:19]
	global_store_dwordx4 v70, v[226:229], s[54:55]
	global_store_dwordx4 v70, v[230:233], s[56:57]
	s_mov_b64 exec, s[20:21]
	global_store_dwordx4 v71, v[234:237], s[54:55]
	global_store_dwordx4 v71, v[238:241], s[56:57]
	s_mov_b64 exec, s[14:15]
	v_add_u32_e32 v3, s10, v204
	v_add_u32_e32 v61, s10, v3
	v_add_u32_e32 v62, s10, v61
	v_add_u32_e32 v63, s10, v62
	s_mov_b64 exec, s[14:15]
	v_cmp_gt_i32_e64 s[6:7], s0, v3
	v_cmp_gt_i32_e64 s[16:17], s0, v61
	v_cmp_gt_i32_e64 s[18:19], s0, v62
	v_cmp_gt_i32_e64 s[20:21], s0, v63
	s_nop 1
	v_min_i32_e32 v64, s3, v3
	v_lshlrev_b32_e32 v64, 5, v64
	global_load_dwordx4 v[72:75], v64, s[40:41]
	global_load_dwordx4 v[76:79], v64, s[40:41] offset:16
	global_load_dwordx4 v[80:83], v64, s[42:43]
	global_load_dwordx4 v[84:87], v64, s[42:43] offset:16
	v_min_i32_e32 v65, s3, v61
	v_lshlrev_b32_e32 v65, 5, v65
	global_load_dwordx4 v[88:91], v65, s[40:41]
	global_load_dwordx4 v[92:95], v65, s[40:41] offset:16
	global_load_dwordx4 v[96:99], v65, s[42:43]
	global_load_dwordx4 v[100:103], v65, s[42:43] offset:16
	v_min_i32_e32 v66, s3, v62
	v_lshlrev_b32_e32 v66, 5, v66
	global_load_dwordx4 v[104:107], v66, s[40:41]
	global_load_dwordx4 v[108:111], v66, s[40:41] offset:16
	global_load_dwordx4 v[112:115], v66, s[42:43]
	global_load_dwordx4 v[116:119], v66, s[42:43] offset:16
	v_min_i32_e32 v67, s3, v63
	v_lshlrev_b32_e32 v67, 5, v67
	global_load_dwordx4 v[120:123], v67, s[40:41]
	global_load_dwordx4 v[124:127], v67, s[40:41] offset:16
	global_load_dwordx4 v[128:131], v67, s[42:43]
	global_load_dwordx4 v[132:135], v67, s[42:43] offset:16
	s_mov_b64 exec, s[14:15]
	v_ashrrev_i32_e32 v242, 17, v3
	v_bfe_u32 v243, v3, 6, 11
	v_mad_u32_u24 v243, v242, s11, v243
	v_and_b32_e32 v242, 63, v3
	v_lshlrev_b32_e32 v242, 4, v242
	v_lshl_add_u32 v68, v243, 10, v242
	v_ashrrev_i32_e32 v242, 17, v61
	v_bfe_u32 v243, v61, 6, 11
	v_mad_u32_u24 v243, v242, s11, v243
	v_and_b32_e32 v242, 63, v61
	v_lshlrev_b32_e32 v242, 4, v242
	v_lshl_add_u32 v69, v243, 10, v242
	v_ashrrev_i32_e32 v242, 17, v62
	v_bfe_u32 v243, v62, 6, 11
	v_mad_u32_u24 v243, v242, s11, v243
	v_and_b32_e32 v242, 63, v62
	v_lshlrev_b32_e32 v242, 4, v242
	v_lshl_add_u32 v70, v243, 10, v242
	v_ashrrev_i32_e32 v242, 17, v63
	v_bfe_u32 v243, v63, 6, 11
	v_mad_u32_u24 v243, v242, s11, v243
	v_and_b32_e32 v242, 63, v63
	v_lshlrev_b32_e32 v242, 4, v242
	v_lshl_add_u32 v71, v243, 10, v242
	s_waitcnt vmcnt(28)
	v_cvt_pk_bf16_f32 v20, v136, v137
	v_cvt_pk_bf16_f32 v21, v138, v139
	v_cvt_pk_bf16_f32 v22, v140, v141
	v_cvt_pk_bf16_f32 v23, v142, v143
	v_cvt_pk_bf16_f32 v24, v144, v145
	v_cvt_pk_bf16_f32 v25, v146, v147
	v_cvt_pk_bf16_f32 v26, v148, v149
	v_cvt_pk_bf16_f32 v27, v150, v151
	s_waitcnt vmcnt(24)
	v_cvt_pk_bf16_f32 v28, v152, v153
	v_cvt_pk_bf16_f32 v29, v154, v155
	v_cvt_pk_bf16_f32 v30, v156, v157
	v_cvt_pk_bf16_f32 v31, v158, v159
	v_cvt_pk_bf16_f32 v32, v160, v161
	v_cvt_pk_bf16_f32 v33, v162, v163
	v_cvt_pk_bf16_f32 v34, v164, v165
	v_cvt_pk_bf16_f32 v35, v166, v167
	s_waitcnt vmcnt(20)
	v_cvt_pk_bf16_f32 v36, v168, v169
	v_cvt_pk_bf16_f32 v37, v170, v171
	v_cvt_pk_bf16_f32 v38, v172, v173
	v_cvt_pk_bf16_f32 v39, v174, v175
	v_cvt_pk_bf16_f32 v40, v176, v177
	v_cvt_pk_bf16_f32 v41, v178, v179
	v_cvt_pk_bf16_f32 v42, v180, v181
	v_cvt_pk_bf16_f32 v43, v182, v183
	s_waitcnt vmcnt(16)
	v_cvt_pk_bf16_f32 v44, v184, v185
	v_cvt_pk_bf16_f32 v45, v186, v187
	v_cvt_pk_bf16_f32 v46, v188, v189
	v_cvt_pk_bf16_f32 v47, v190, v191
	v_cvt_pk_bf16_f32 v48, v192, v193
	v_cvt_pk_bf16_f32 v49, v194, v195
	v_cvt_pk_bf16_f32 v50, v196, v197
	v_cvt_pk_bf16_f32 v51, v198, v199
	s_mov_b64 exec, s[22:23]
	global_store_dwordx4 v205, v[20:23], s[54:55]
	global_store_dwordx4 v205, v[24:27], s[56:57]
	s_mov_b64 exec, s[24:25]
	global_store_dwordx4 v206, v[28:31], s[54:55]
	global_store_dwordx4 v206, v[32:35], s[56:57]
	s_mov_b64 exec, s[26:27]
	global_store_dwordx4 v207, v[36:39], s[54:55]
	global_store_dwordx4 v207, v[40:43], s[56:57]
	s_mov_b64 exec, s[30:31]
	global_store_dwordx4 v209, v[44:47], s[54:55]
	global_store_dwordx4 v209, v[48:51], s[56:57]
	s_mov_b64 exec, s[14:15]
	s_waitcnt vmcnt(12)
	v_cvt_pk_bf16_f32 v210, v72, v73
	v_cvt_pk_bf16_f32 v211, v74, v75
	v_cvt_pk_bf16_f32 v212, v76, v77
	v_cvt_pk_bf16_f32 v213, v78, v79
	v_cvt_pk_bf16_f32 v214, v80, v81
	v_cvt_pk_bf16_f32 v215, v82, v83
	v_cvt_pk_bf16_f32 v216, v84, v85
	v_cvt_pk_bf16_f32 v217, v86, v87
	s_waitcnt vmcnt(8)
	v_cvt_pk_bf16_f32 v218, v88, v89
	v_cvt_pk_bf16_f32 v219, v90, v91
	v_cvt_pk_bf16_f32 v220, v92, v93
	v_cvt_pk_bf16_f32 v221, v94, v95
	v_cvt_pk_bf16_f32 v222, v96, v97
	v_cvt_pk_bf16_f32 v223, v98, v99
	v_cvt_pk_bf16_f32 v224, v100, v101
	v_cvt_pk_bf16_f32 v225, v102, v103
	s_waitcnt vmcnt(4)
	v_cvt_pk_bf16_f32 v226, v104, v105
	v_cvt_pk_bf16_f32 v227, v106, v107
	v_cvt_pk_bf16_f32 v228, v108, v109
	v_cvt_pk_bf16_f32 v229, v110, v111
	v_cvt_pk_bf16_f32 v230, v112, v113
	v_cvt_pk_bf16_f32 v231, v114, v115
	v_cvt_pk_bf16_f32 v232, v116, v117
	v_cvt_pk_bf16_f32 v233, v118, v119
	s_waitcnt vmcnt(0)
	v_cvt_pk_bf16_f32 v234, v120, v121
	v_cvt_pk_bf16_f32 v235, v122, v123
	v_cvt_pk_bf16_f32 v236, v124, v125
	v_cvt_pk_bf16_f32 v237, v126, v127
	v_cvt_pk_bf16_f32 v238, v128, v129
	v_cvt_pk_bf16_f32 v239, v130, v131
	v_cvt_pk_bf16_f32 v240, v132, v133
	v_cvt_pk_bf16_f32 v241, v134, v135
	s_mov_b64 exec, s[6:7]
	global_store_dwordx4 v68, v[210:213], s[54:55]
	global_store_dwordx4 v68, v[214:217], s[56:57]
	s_mov_b64 exec, s[16:17]
	global_store_dwordx4 v69, v[218:221], s[54:55]
	global_store_dwordx4 v69, v[222:225], s[56:57]
	s_mov_b64 exec, s[18:19]
	global_store_dwordx4 v70, v[226:229], s[54:55]
	global_store_dwordx4 v70, v[230:233], s[56:57]
	s_mov_b64 exec, s[20:21]
	global_store_dwordx4 v71, v[234:237], s[54:55]
	global_store_dwordx4 v71, v[238:241], s[56:57]
	s_mov_b64 exec, s[14:15]
